# v30 + GEMM accumulator zeroing with v_mov_b64 pairs
# speedup vs baseline: 1.0168x; 1.0084x over previous
.LBB0_299:
	s_ashr_i32 s63, s62, 31
	s_lshl_b64 s[0:1], s[62:63], 19
	s_add_u32 s66, s43, s0
	s_addc_u32 s67, s55, s1
	s_and_b64 s[0:1], s[64:65], exec
	s_cselect_b32 s7, s67, s71
	s_cselect_b32 s9, s66, s70
	s_ashr_i32 s61, s60, 31
	s_lshl_b64 s[0:1], s[60:61], 19
	s_add_u32 s68, s59, s0
	s_addc_u32 s69, s74, s1
	s_and_b64 s[0:1], s[64:65], exec
	s_cselect_b32 s16, s69, s11
	s_cselect_b32 s33, s68, s10
	s_add_u32 s0, s70, 0x40080
	s_addc_u32 s1, s71, 0
	s_add_u32 s61, s10, 0x100
	v_mov_b32_e32 v4, 0
	s_addc_u32 s63, s11, 0
	s_mov_b32 s70, -2
	v_mov_b32_e32 v5, v4
	v_mov_b64_e32 v[6:7], 0
	v_mov_b64_e32 v[8:9], 0
	v_mov_b64_e32 v[10:11], 0
	v_mov_b64_e32 v[12:13], 0
	v_mov_b64_e32 v[14:15], 0
	v_mov_b64_e32 v[16:17], 0
	v_mov_b64_e32 v[18:19], 0
	v_mov_b64_e32 v[20:21], 0
	v_mov_b64_e32 v[22:23], 0
	v_mov_b64_e32 v[24:25], 0
	v_mov_b64_e32 v[26:27], 0
	v_mov_b64_e32 v[28:29], 0
	v_mov_b64_e32 v[30:31], 0
	v_mov_b64_e32 v[32:33], 0
	v_mov_b64_e32 v[34:35], 0
	v_mov_b64_e32 v[68:69], 0
	v_mov_b64_e32 v[70:71], 0
	v_mov_b64_e32 v[72:73], 0
	v_mov_b64_e32 v[74:75], 0
	v_mov_b64_e32 v[76:77], 0
	v_mov_b64_e32 v[78:79], 0
	v_mov_b64_e32 v[80:81], 0
	v_mov_b64_e32 v[82:83], 0
	v_mov_b64_e32 v[84:85], 0
	v_mov_b64_e32 v[86:87], 0
	v_mov_b64_e32 v[88:89], 0
	v_mov_b64_e32 v[90:91], 0
	v_mov_b64_e32 v[92:93], 0
	v_mov_b64_e32 v[94:95], 0
	v_mov_b64_e32 v[96:97], 0
	v_mov_b64_e32 v[98:99], 0
	v_mov_b64_e32 v[36:37], 0
	v_mov_b64_e32 v[38:39], 0
	v_mov_b64_e32 v[40:41], 0
	v_mov_b64_e32 v[42:43], 0
	v_mov_b64_e32 v[44:45], 0
	v_mov_b64_e32 v[46:47], 0
	v_mov_b64_e32 v[48:49], 0
	v_mov_b64_e32 v[50:51], 0
	v_mov_b64_e32 v[52:53], 0
	v_mov_b64_e32 v[54:55], 0
	v_mov_b64_e32 v[56:57], 0
	v_mov_b64_e32 v[58:59], 0
	v_mov_b64_e32 v[60:61], 0
	v_mov_b64_e32 v[62:63], 0
	v_mov_b64_e32 v[64:65], 0
	v_mov_b64_e32 v[66:67], 0
	v_mov_b64_e32 v[100:101], 0
	v_mov_b64_e32 v[102:103], 0
	v_mov_b64_e32 v[104:105], 0
	v_mov_b64_e32 v[106:107], 0
	v_mov_b64_e32 v[108:109], 0
	v_mov_b64_e32 v[110:111], 0
	v_mov_b64_e32 v[112:113], 0
	v_mov_b64_e32 v[114:115], 0
	v_mov_b64_e32 v[116:117], 0
	v_mov_b64_e32 v[118:119], 0
	v_mov_b64_e32 v[120:121], 0
	v_mov_b64_e32 v[122:123], 0
	v_mov_b64_e32 v[124:125], 0
	v_mov_b64_e32 v[126:127], 0
	v_mov_b64_e32 v[128:129], 0
	v_mov_b64_e32 v[130:131], 0

.LBB0_737:
	s_add_i32 s38, s38, 1
	s_mul_i32 s6, s38, s57
	s_mul_hi_u32 s7, s38, s56
	s_add_i32 s7, s7, s6
	s_mul_i32 s6, s38, s56
	v_readlane_b32 s8, v254, 14
	v_readlane_b32 s9, v254, 15
	s_add_u32 s8, s6, s8
	s_addc_u32 s9, s7, s9
	v_cmp_lt_i64_e64 s[6:7], s[8:9], v[212:213]
	v_cmp_lt_i64_e64 s[12:13], s[8:9], 64
	s_sub_i32 s9, s8, 64
	s_and_b64 s[12:13], s[12:13], exec
	s_mov_b64 s[2:3], s[26:27]
	s_mov_b32 s22, s20
	s_mov_b32 s26, s78
	s_mov_b32 s10, s20
	s_mov_b32 s11, s78
	s_cselect_b32 s20, s8, s9
	s_cselect_b32 s78, 20, 19
	s_and_b64 s[8:9], s[6:7], exec
	s_cselect_b32 s12, s20, s22
	s_cselect_b32 s8, s78, s26
	s_ashr_i32 s13, s12, 31
	s_lshl_b64 s[12:13], s[12:13], 19
	s_mov_b64 s[0:1], s[28:29]
	s_add_u32 s28, s55, s12
	s_addc_u32 s29, s69, s13
	s_and_b64 s[12:13], s[6:7], exec
	s_cselect_b32 s12, s29, s1
	s_cselect_b32 s13, s28, s0
	s_ashr_i32 s9, s8, 31
	s_lshl_b64 s[8:9], s[8:9], 19
	s_add_u32 s26, s71, s8
	s_addc_u32 s27, s76, s9
	s_and_b64 s[8:9], s[6:7], exec
	s_cselect_b32 s22, s27, s3
	s_cselect_b32 s33, s26, s2
	s_add_u32 s0, s0, 0x40080
	s_addc_u32 s1, s1, 0
	s_add_u32 s39, s2, 0x100
	v_mov_b32_e32 v4, 0
	s_addc_u32 s72, s3, 0
	s_mov_b32 s73, -2
	v_mov_b32_e32 v5, v4
	v_mov_b64_e32 v[6:7], 0
	v_mov_b64_e32 v[8:9], 0
	v_mov_b64_e32 v[10:11], 0
	v_mov_b64_e32 v[12:13], 0
	v_mov_b64_e32 v[14:15], 0
	v_mov_b64_e32 v[16:17], 0
	v_mov_b64_e32 v[18:19], 0
	v_mov_b64_e32 v[20:21], 0
	v_mov_b64_e32 v[22:23], 0
	v_mov_b64_e32 v[24:25], 0
	v_mov_b64_e32 v[26:27], 0
	v_mov_b64_e32 v[28:29], 0
	v_mov_b64_e32 v[30:31], 0
	v_mov_b64_e32 v[32:33], 0
	v_mov_b64_e32 v[34:35], 0
	v_mov_b64_e32 v[68:69], 0
	v_mov_b64_e32 v[70:71], 0
	v_mov_b64_e32 v[72:73], 0
	v_mov_b64_e32 v[74:75], 0
	v_mov_b64_e32 v[76:77], 0
	v_mov_b64_e32 v[78:79], 0
	v_mov_b64_e32 v[80:81], 0
	v_mov_b64_e32 v[82:83], 0
	v_mov_b64_e32 v[84:85], 0
	v_mov_b64_e32 v[86:87], 0
	v_mov_b64_e32 v[88:89], 0
	v_mov_b64_e32 v[90:91], 0
	v_mov_b64_e32 v[92:93], 0
	v_mov_b64_e32 v[94:95], 0
	v_mov_b64_e32 v[96:97], 0
	v_mov_b64_e32 v[98:99], 0
	v_mov_b64_e32 v[36:37], 0
	v_mov_b64_e32 v[38:39], 0
	v_mov_b64_e32 v[40:41], 0
	v_mov_b64_e32 v[42:43], 0
	v_mov_b64_e32 v[44:45], 0
	v_mov_b64_e32 v[46:47], 0
	v_mov_b64_e32 v[48:49], 0
	v_mov_b64_e32 v[50:51], 0
	v_mov_b64_e32 v[52:53], 0
	v_mov_b64_e32 v[54:55], 0
	v_mov_b64_e32 v[56:57], 0
	v_mov_b64_e32 v[58:59], 0
	v_mov_b64_e32 v[60:61], 0
	v_mov_b64_e32 v[62:63], 0
	v_mov_b64_e32 v[64:65], 0
	v_mov_b64_e32 v[66:67], 0
	v_mov_b64_e32 v[100:101], 0
	v_mov_b64_e32 v[102:103], 0
	v_mov_b64_e32 v[104:105], 0
	v_mov_b64_e32 v[106:107], 0
	v_mov_b64_e32 v[108:109], 0
	v_mov_b64_e32 v[110:111], 0
	v_mov_b64_e32 v[112:113], 0
	v_mov_b64_e32 v[114:115], 0
	v_mov_b64_e32 v[116:117], 0
	v_mov_b64_e32 v[118:119], 0
	v_mov_b64_e32 v[120:121], 0
	v_mov_b64_e32 v[122:123], 0
	v_mov_b64_e32 v[124:125], 0
	v_mov_b64_e32 v[126:127], 0
	v_mov_b64_e32 v[128:129], 0
	v_mov_b64_e32 v[130:131], 0
